# plus XCD-leader early invalidate (after its write-back, before the top-level arrive)
# baseline (speedup 1.0000x reference)
; __device__ __forceinline__ unsigned xb_ld(unsigned* p)              { return __hip_atomic_load(p, __ATOMIC_RELAXED, __HIP_MEMORY_SCOPE_AGENT); }
; __device__ __forceinline__ unsigned xb_add(unsigned* p, unsigned v) { return __hip_atomic_fetch_add(p, v, __ATOMIC_RELAXED, __HIP_MEMORY_SCOPE_AGENT); }
; #define XB_SPIN(cond, bar) do { unsigned _sp = 0; while (cond) { __builtin_amdgcn_s_sleep(1); \
;     if ((++_sp & 255u) == 0u) { if (xb_ld(&(bar)[XB_TMO])) break; if (_sp > XB_SPIN_CAP) { atomicAdd(&(bar)[XB_TMO], 1u); break; } } } } while (0)
; __device__ __forceinline__ void xcd_barrier(const XcdBarrier& b, int tid) {
;     ...
;             asm volatile("s_waitcnt vmcnt(0)" ::: "memory");
;             const unsigned og = xb_add(&bar[XB_TOP], 1u);
;             const unsigned tg = og / nx;
;             if (og + 1u == (tg + 1u) * nx) xb_add(&bar[XB_TOPGEN], 1u);
;             else XB_SPIN(xb_ld(&bar[XB_TOPGEN]) == tg, bar);
.LBB0_1040:
	s_or_b64 exec, exec, s[12:13]
	buffer_inv sc1
	s_waitcnt vmcnt(1)
	v_readfirstlane_b32 s4, v2
	v_cvt_f32_u32_e32 v2, v0
	v_sub_u32_e32 v3, 0, v0
	v_add_u32_e32 v1, s4, v1
	v_readlane_b32 s10, v254, 44
	v_rcp_iflag_f32_e32 v2, v2
	v_readlane_b32 s11, v254, 45
	s_mov_b64 s[12:13], -1
	v_mul_f32_e32 v2, 0x4f7ffffe, v2
	v_cvt_u32_f32_e32 v2, v2
	v_mul_lo_u32 v3, v3, v2
	v_mul_hi_u32 v3, v2, v3
	v_add_u32_e32 v2, v2, v3
	v_mul_hi_u32 v2, v1, v2
	v_mul_lo_u32 v3, v2, v0
	v_sub_u32_e32 v3, v1, v3
	v_cmp_ge_u32_e32 vcc, v3, v0
	v_add_u32_e32 v4, 1, v2
	v_add_u32_e32 v1, 1, v1
	v_cndmask_b32_e32 v2, v2, v4, vcc
	v_sub_u32_e32 v4, v3, v0
	v_cndmask_b32_e32 v3, v3, v4, vcc
	v_cmp_ge_u32_e32 vcc, v3, v0
	v_add_u32_e32 v3, 1, v2
	s_nop 0
	v_cndmask_b32_e32 v2, v2, v3, vcc
	v_mul_lo_u32 v3, v0, v2
	v_add_u32_e32 v0, v3, v0
	v_cmp_ne_u32_e32 vcc, v1, v0
	v_mov_b64_e32 v[0:1], s[10:11]
	s_and_saveexec_b64 s[10:11], vcc
	s_cbranch_execz .LBB0_1052
	v_readlane_b32 s12, v254, 44
	v_readlane_b32 s13, v254, 45
	s_mov_b64 s[14:15], 0
	s_nop 3
	global_load_dword v0, v169, s[12:13] sc1
	s_waitcnt vmcnt(0)
	v_cmp_eq_u32_e32 vcc, v0, v2
	s_and_saveexec_b64 s[12:13], vcc
	s_cbranch_execz .LBB0_1051
	s_mov_b32 s4, 1
	s_branch .LBB0_1044

; __device__ __forceinline__ unsigned xb_add(unsigned* p, unsigned v) { return __hip_atomic_fetch_add(p, v, __ATOMIC_RELAXED, __HIP_MEMORY_SCOPE_AGENT); }
; __device__ __forceinline__ void xcd_barrier(const XcdBarrier& b, int tid) {
;     ...
;             __builtin_amdgcn_fence(__ATOMIC_ACQUIRE, "agent");
;             xb_add(&bar[XB_XGEN(b.x)], 1u);
.LBB0_1054:
	s_or_b64 exec, exec, s[10:11]
	s_mov_b64 s[10:11], exec
	v_mbcnt_lo_u32_b32 v0, s10, 0
	v_mbcnt_hi_u32_b32 v0, s11, v0
	v_cmp_eq_u32_e32 vcc, 0, v0
	s_waitcnt vmcnt(0)
	s_nop 0
	s_and_saveexec_b64 s[12:13], vcc
	s_cbranch_execnz .LBB0_1055
	s_getpc_b64 s[98:99]
